# v40 + static s_setprio 1 for waves 4-7 during the layer-B sliding-window attention phase
# speedup vs baseline: 1.0023x; 1.0023x over previous
.LBB0_92:
	s_andn2_b64 vcc, exec, s[4:5]
	s_cbranch_vccnz .LBB0_613
	s_waitcnt lgkmcnt(0)
	v_mul_u32_u24_e32 v4, 0x90, v177
	v_lshlrev_b32_e32 v16, 4, v184
	s_mov_b32 s10, 0x66666667
	v_add3_u32 v144, 0, v4, v16
	v_mul_hi_i32 v4, v176, s10
	v_lshrrev_b32_e32 v5, 31, v4
	v_ashrrev_i32_e32 v4, 3, v4
	v_add_u32_e32 v9, v4, v5
	s_movk_i32 s13, 0x150
	v_mul_lo_u32 v7, v9, s13
	v_add_u32_e32 v8, 0x200, v176
	v_add_u32_e32 v18, 0, v7
	v_mul_hi_i32 v7, v8, s10
	v_lshrrev_b32_e32 v10, 31, v7
	v_ashrrev_i32_e32 v7, 3, v7
	v_add_u32_e32 v13, v7, v10
	v_mul_lo_u32 v7, v13, s13
	v_add_u32_e32 v12, 0x400, v176
	v_add_u32_e32 v20, 0, v7
	v_mul_hi_i32 v7, v12, s10
	v_lshrrev_b32_e32 v14, 31, v7
	v_ashrrev_i32_e32 v7, 3, v7
	s_movk_i32 s11, 0xffec
	v_add_u32_e32 v22, v7, v14
	v_readlane_b32 s4, v252, 62
	v_lshlrev_b32_e32 v0, 4, v176
	v_mad_u64_u32 v[4:5], s[6:7], v9, s11, v[176:177]
	v_ashrrev_i32_e32 v6, 3, v176
	s_movk_i32 s12, 0x90
	v_mad_u64_u32 v[10:11], s[8:9], v13, s11, v[8:9]
	v_ashrrev_i32_e32 v8, 3, v8
	v_mad_u64_u32 v[14:15], s[10:11], v22, s11, v[12:13]
	v_ashrrev_i32_e32 v12, 3, v12
	s_mulk_i32 s4, 0x1200
	v_and_b32_e32 v0, 0x70, v0
	v_mul_lo_u32 v5, v6, s12
	v_mul_lo_u32 v11, v8, s12
	v_mul_lo_u32 v15, v12, s12
	s_movk_i32 s12, 0x1080
	s_add_i32 s19, s4, 0
	v_add_u32_e32 v3, 0, v0
	v_lshlrev_b32_e32 v0, 3, v176
	v_readlane_b32 s4, v252, 63
	v_mul_lo_u32 v7, v22, s13
	v_mad_i64_i32 v[108:109], s[10:11], v9, s12, 0
	v_mad_i64_i32 v[114:115], s[10:11], v13, s12, 0
	v_mad_i64_i32 v[120:121], s[10:11], v22, s12, 0
	v_and_b32_e32 v0, 56, v0
	s_and_b32 s20, s4, 0xffffffc0
	v_lshlrev_b32_e32 v2, 3, v184
	v_mul_u32_u24_e32 v17, 0x150, v177
	s_movk_i32 s4, 0x500
	v_lshlrev_b32_e32 v19, 4, v4
	s_movk_i32 s6, 0x300
	v_lshlrev_b32_e32 v21, 4, v10
	s_movk_i32 s8, 0x100
	v_add_u32_e32 v23, 0, v7
	v_lshlrev_b32_e32 v24, 4, v14
	v_ashrrev_i32_e32 v7, 31, v6
	v_lshlrev_b32_e32 v110, 3, v4
	v_ashrrev_i32_e32 v9, 31, v8
	v_lshlrev_b32_e32 v116, 3, v10
	v_ashrrev_i32_e32 v13, 31, v12
	v_lshlrev_b32_e32 v122, 3, v14
	v_readlane_b32 s10, v252, 25
	v_lshlrev_b32_e32 v145, 2, v184
	v_cmp_gt_i32_e64 s[4:5], s4, v176
	v_cmp_gt_i32_e64 s[6:7], s6, v176
	v_cmp_gt_i32_e64 s[8:9], s8, v176
	v_lshlrev_b64 v[106:107], 9, v[6:7]
	v_ashrrev_i32_e32 v111, 31, v110
	v_lshlrev_b64 v[112:113], 9, v[8:9]
	v_ashrrev_i32_e32 v117, 31, v116
	v_lshlrev_b64 v[118:119], 9, v[12:13]
	v_ashrrev_i32_e32 v123, 31, v122
	v_add3_u32 v146, v17, v16, s10
	s_mov_b32 s21, 0
	v_add_u32_e32 v147, v3, v5
	v_add_u32_e32 v148, v18, v19
	v_add_u32_e32 v149, v3, v11
	v_add_u32_e32 v150, v20, v21
	v_add_u32_e32 v151, v3, v15
	v_add_u32_e32 v152, v23, v24
	v_lshlrev_b32_e32 v0, 1, v0
	v_lshlrev_b32_e32 v124, 1, v2
	s_mov_b32 s23, s79
	s_cmp_eq_u32 s98, 0
	s_cbranch_scc1 .Lmy_prio_b
	s_setprio 1
.Lmy_prio_b:
	s_branch .LBB0_583

.LBB0_613:
	s_setprio 0
	s_mov_b64 s[4:5], 0
